# speedup vs baseline: 1.0013x; 1.0013x over previous
; __device__ __forceinline__ unsigned cvt_pk_bf16(float lo, float hi) { unsigned r; asm("v_cvt_pk_bf16_f32 %0, %1, %2" : "=v"(r) : "v"(lo), "v"(hi)); return r; }
; __device__ __forceinline__ void attn_unit(int layer, int sample, int b, int c, int hp, unsigned char* shm) {
;     ...
;             mloc = fmaxf(mloc, __shfl_xor(mloc, 16)); mloc = fmaxf(mloc, __shfl_xor(mloc, 32));
;             const float mnew = fmaxf(mrun, mloc), alpha = __expf(mrun - mnew);
;             mrun = mnew; float ls = 0.f;
; #pragma unroll
;             for (int sub = 0; sub < 4; ++sub)
; #pragma unroll
;                 for (int j = 0; j < 4; ++j) { const float e = __expf(s[sub][j] - mnew); s[sub][j] = e; ls += e; }
;             lrun = lrun * alpha + ls;
; #pragma unroll
;             for (int d = 0; d < 8; ++d) ao[d] *= alpha;
; #pragma unroll
;             for (int pr = 0; pr < 2; ++pr) {
;                 u32x4 pk; pk[0] = cvt_pk_bf16(s[2 * pr][0], s[2 * pr][1]); pk[1] = cvt_pk_bf16(s[2 * pr][2], s[2 * pr][3]);
;                 pk[2] = cvt_pk_bf16(s[2 * pr + 1][0], s[2 * pr + 1][1]); pk[3] = cvt_pk_bf16(s[2 * pr + 1][2], s[2 * pr + 1][3]);
;                 const bf16x8 bfrag = *(const bf16x8*)&pk;
; #pragma unroll
;                 for (int d = 0; d < 8; ++d) {
;                     const u32x2 lo = *(const u32x2*)(VT + (d * 16 + fr) * 72 + (2 * pr) * 16 + fq * 4);
;                     const u32x2 hi = *(const u32x2*)(VT + (d * 16 + fr) * 72 + (2 * pr + 1) * 16 + fq * 4);
;                     u32x4 av; av[0] = lo[0]; av[1] = lo[1]; av[2] = hi[0]; av[3] = hi[1];
;                     ao[d] = __builtin_amdgcn_mfma_f32_16x16x32_bf16(*(const bf16x8*)&av, bfrag, ao[d], 0, 0, 0);
;                 }
;             }
.LBB0_801:
	v_and_b32_e32 v35, 64, v227
	v_xor_b32_e32 v34, 16, v227
	v_add_u32_e32 v35, 64, v35
	v_cmp_lt_i32_e32 vcc, v34, v35
	s_nop 1
	v_cndmask_b32_e32 v34, v227, v34, vcc
	v_lshlrev_b32_e32 v34, 2, v34
	ds_bpermute_b32 v34, v34, v1
	v_max_f32_e32 v1, v1, v1
	s_waitcnt lgkmcnt(0)
	v_max_f32_e32 v34, v34, v34
	v_max_f32_e32 v1, v1, v34
	v_xor_b32_e32 v34, 32, v227
	v_cmp_lt_i32_e32 vcc, v34, v35
	s_nop 1
	v_cndmask_b32_e32 v34, v227, v34, vcc
	v_lshlrev_b32_e32 v34, 2, v34
	ds_bpermute_b32 v34, v34, v1
	s_waitcnt lgkmcnt(0)
	v_max3_f32 v1, v191, v1, v34
	v_sub_f32_e32 v36, v57, v1
	v_mul_f32_e32 v36, 0x3fb8aa3b, v36
	v_exp_f32_e32 v39, v36
	v_sub_f32_e32 v36, v54, v1
	v_mul_f32_e32 v36, 0x3fb8aa3b, v36
	v_exp_f32_e32 v40, v36
	v_sub_f32_e32 v36, v55, v1
	v_mul_f32_e32 v36, 0x3fb8aa3b, v36
	v_exp_f32_e32 v41, v36
	v_sub_f32_e32 v36, v52, v1
	v_mul_f32_e32 v36, 0x3fb8aa3b, v36
	v_exp_f32_e32 v171, v36
	v_sub_f32_e32 v36, v53, v1
	v_sub_f32_e32 v35, v56, v1
	v_mul_f32_e32 v36, 0x3fb8aa3b, v36
	v_mul_f32_e32 v35, 0x3fb8aa3b, v35
	v_exp_f32_e32 v173, v36
	v_sub_f32_e32 v36, v50, v1
	v_exp_f32_e32 v38, v35
	v_mul_f32_e32 v36, 0x3fb8aa3b, v36
	v_sub_f32_e32 v34, v191, v1
	v_exp_f32_e32 v191, v36
	v_sub_f32_e32 v36, v51, v1
	v_mul_f32_e32 v36, 0x3fb8aa3b, v36
	v_exp_f32_e32 v192, v36
	v_sub_f32_e32 v36, v60, v1
	v_add_f32_e32 v35, 0, v38
	v_mul_f32_e32 v36, 0x3fb8aa3b, v36
	v_add_f32_e32 v35, v39, v35
	v_exp_f32_e32 v193, v36
	v_sub_f32_e32 v36, v61, v1
	v_add_f32_e32 v35, v40, v35
	v_mul_f32_e32 v36, 0x3fb8aa3b, v36
	v_add_f32_e32 v35, v41, v35
	v_exp_f32_e32 v194, v36
	v_sub_f32_e32 v36, v58, v1
	v_add_f32_e32 v35, v171, v35
	v_mul_f32_e32 v36, 0x3fb8aa3b, v36
	v_add_f32_e32 v35, v173, v35
	v_exp_f32_e32 v195, v36
	v_sub_f32_e32 v36, v59, v1
	v_add_f32_e32 v35, v191, v35
	v_mul_f32_e32 v36, 0x3fb8aa3b, v36
	v_mul_f32_e32 v34, 0x3fb8aa3b, v34
	v_add_f32_e32 v35, v192, v35
	v_exp_f32_e32 v196, v36
	v_add_f32_e32 v35, v193, v35
	v_exp_f32_e32 v42, v34
	v_add_f32_e32 v35, v194, v35
	v_add_f32_e32 v35, v195, v35
	v_add_f32_e32 v43, v196, v35
	v_add_u32_e32 v204, 0x8800, v181
	v_add_u32_e32 v205, 0x8800, v182
	v_add_u32_e32 v206, 0x8800, v183
	v_add_u32_e32 v207, 0x8800, v184
	v_add_u32_e32 v208, 0xa800, v181
	v_add_u32_e32 v209, 0xb000, v181
	v_add_u32_e32 v210, 0xb800, v181
	v_add_u32_e32 v211, 0xc000, v181
	ds_read2_b64 v[228:231], v204 offset1:4
	ds_read2_b64 v[232:235], v205 offset1:4
	ds_read2_b64 v[236:239], v206 offset1:4
	ds_read2_b64 v[240:243], v207 offset1:4
	ds_read2_b64 v[244:247], v208 offset0:128 offset1:132
	ds_read2_b64 v[248:251], v209 offset0:160 offset1:164
	ds_read2_b64 v[44:47], v210 offset0:192 offset1:196
	ds_read2_b64 v[48:51], v211 offset0:224 offset1:228
	ds_read2_b64 v[52:55], v204 offset0:8 offset1:12
	ds_read2_b64 v[56:59], v205 offset0:8 offset1:12
	v_pk_mul_f32 v[114:115], v[114:115], v[42:43] op_sel_hi:[1,0]
	v_pk_mul_f32 v[116:117], v[116:117], v[42:43] op_sel_hi:[1,0]
	v_pk_mul_f32 v[118:119], v[118:119], v[42:43] op_sel_hi:[1,0]
	v_pk_mul_f32 v[120:121], v[120:121], v[42:43] op_sel_hi:[1,0]
	v_pk_mul_f32 v[122:123], v[122:123], v[42:43] op_sel_hi:[1,0]
	v_pk_mul_f32 v[124:125], v[124:125], v[42:43] op_sel_hi:[1,0]
	v_pk_mul_f32 v[126:127], v[126:127], v[42:43] op_sel_hi:[1,0]
	v_pk_mul_f32 v[128:129], v[128:129], v[42:43] op_sel_hi:[1,0]
	v_pk_mul_f32 v[130:131], v[130:131], v[42:43] op_sel_hi:[1,0]
	v_pk_mul_f32 v[132:133], v[132:133], v[42:43] op_sel_hi:[1,0]
	v_pk_mul_f32 v[134:135], v[134:135], v[42:43] op_sel_hi:[1,0]
	v_pk_mul_f32 v[136:137], v[136:137], v[42:43] op_sel_hi:[1,0]
	v_pk_mul_f32 v[138:139], v[138:139], v[42:43] op_sel_hi:[1,0]
	v_pk_mul_f32 v[140:141], v[140:141], v[42:43] op_sel_hi:[1,0]
	v_pk_mul_f32 v[142:143], v[142:143], v[42:43] op_sel_hi:[1,0]
	v_pk_mul_f32 v[144:145], v[144:145], v[42:43] op_sel_hi:[1,0]
	v_cvt_pk_bf16_f32 v38, v38, v39
	v_cvt_pk_bf16_f32 v39, v40, v41
	v_cvt_pk_bf16_f32 v40, v171, v173
	v_cvt_pk_bf16_f32 v41, v191, v192
	v_sub_f32_e32 v35, v62, v1
	v_mul_f32_e32 v35, 0x3fb8aa3b, v35
	v_exp_f32_e32 v197, v35
	v_sub_f32_e32 v35, v63, v1
	v_mul_f32_e32 v35, 0x3fb8aa3b, v35
	v_exp_f32_e32 v198, v35
	v_sub_f32_e32 v35, v64, v1
	v_mul_f32_e32 v35, 0x3fb8aa3b, v35
	v_exp_f32_e32 v64, v35
	v_sub_f32_e32 v35, v65, v1
	v_mul_f32_e32 v35, 0x3fb8aa3b, v35
	v_exp_f32_e32 v65, v35
	s_nop 0
	v_add_f32_e32 v43, v197, v43
	v_add_f32_e32 v43, v198, v43
	v_add_f32_e32 v43, v64, v43
	v_add_f32_e32 v43, v65, v43
	v_cvt_pk_bf16_f32 v200, v193, v194
	v_cvt_pk_bf16_f32 v201, v195, v196
	v_cvt_pk_bf16_f32 v202, v197, v198
	v_cvt_pk_bf16_f32 v203, v64, v65
	v_fmac_f32_e32 v43, v187, v42
	v_mov_b32_e32 v191, v1
	v_mov_b32_e32 v187, v43
	s_waitcnt lgkmcnt(9)
	v_mfma_f32_16x16x32_bf16 v[114:117], v[228:231], v[38:41], v[114:117]
	ds_read2_b64 v[228:231], v206 offset0:8 offset1:12
	s_waitcnt lgkmcnt(9)
	v_mfma_f32_16x16x32_bf16 v[118:121], v[232:235], v[38:41], v[118:121]
	ds_read2_b64 v[232:235], v207 offset0:8 offset1:12
	s_waitcnt lgkmcnt(9)
	v_mfma_f32_16x16x32_bf16 v[122:125], v[236:239], v[38:41], v[122:125]
	ds_read2_b64 v[236:239], v208 offset0:136 offset1:140
	s_waitcnt lgkmcnt(9)
	v_mfma_f32_16x16x32_bf16 v[126:129], v[240:243], v[38:41], v[126:129]
	ds_read2_b64 v[240:243], v209 offset0:168 offset1:172
	s_waitcnt lgkmcnt(9)
	v_mfma_f32_16x16x32_bf16 v[130:133], v[244:247], v[38:41], v[130:133]
	ds_read2_b64 v[244:247], v210 offset0:200 offset1:204
	s_waitcnt lgkmcnt(9)
	v_mfma_f32_16x16x32_bf16 v[134:137], v[248:251], v[38:41], v[134:137]
	ds_read2_b64 v[248:251], v211 offset0:232 offset1:236
	s_waitcnt lgkmcnt(9)
	v_mfma_f32_16x16x32_bf16 v[138:141], v[44:47], v[38:41], v[138:141]
	s_waitcnt lgkmcnt(8)
	v_mfma_f32_16x16x32_bf16 v[142:145], v[48:51], v[38:41], v[142:145]
	s_waitcnt lgkmcnt(7)
	v_mfma_f32_16x16x32_bf16 v[114:117], v[52:55], v[200:203], v[114:117]
	s_waitcnt lgkmcnt(6)
	v_mfma_f32_16x16x32_bf16 v[118:121], v[56:59], v[200:203], v[118:121]
	s_waitcnt lgkmcnt(5)
	v_mfma_f32_16x16x32_bf16 v[122:125], v[228:231], v[200:203], v[122:125]
	s_waitcnt lgkmcnt(4)
	v_mfma_f32_16x16x32_bf16 v[126:129], v[232:235], v[200:203], v[126:129]
	s_waitcnt lgkmcnt(3)
	v_mfma_f32_16x16x32_bf16 v[130:133], v[236:239], v[200:203], v[130:133]
	s_waitcnt lgkmcnt(2)
	v_mfma_f32_16x16x32_bf16 v[134:137], v[240:243], v[200:203], v[134:137]
	s_waitcnt lgkmcnt(1)
	v_mfma_f32_16x16x32_bf16 v[138:141], v[244:247], v[200:203], v[138:141]
	s_waitcnt lgkmcnt(0)
	v_mfma_f32_16x16x32_bf16 v[142:145], v[248:251], v[200:203], v[142:145]

; __device__ __forceinline__ void attn_unit(int layer, int sample, int b, int c, int hp, unsigned char* shm) {
;     ...
;         if (active) {
;             f32x4 s[4];
; #pragma unroll
;             for (int sub = 0; sub < 4; ++sub) { s[sub] = (f32x4){0.f, 0.f, 0.f, 0.f};
; #pragma unroll
;                 for (int k0 = 0; k0 < 4; ++k0) { const bf16x8 a = *(const bf16x8*)(Kt + (sub * 16 + fr) * 136 + k0 * 32 + fq * 8);
;                     s[sub] = __builtin_amdgcn_mfma_f32_16x16x32_bf16(a, qf[k0], s[sub], 0, 0, 0); } }
;             const int kbase = sample ? (4096 - 512 + kt * 64) : ck * 64;
;             float mloc = -1e30f;
;             if (kt <= 5) {
;                 const float bfar = btab[256];
; #pragma unroll
;                 for (int sub = 0; sub < 4; ++sub)
; #pragma unroll
;                     for (int j = 0; j < 4; ++j) { const float v = s[sub][j] + bfar; s[sub][j] = v; mloc = fmaxf(mloc, v); }
;             } else {
; #pragma unroll
;             for (int sub = 0; sub < 4; ++sub)
; #pragma unroll
;                 for (int j = 0; j < 4; ++j) { const int kl = sub * 16 + fq * 4 + j; int rel = qpos - (kbase + kl); rel = rel < -128 ? -128 : (rel > 128 ? 128 : rel);
;                     float v = s[sub][j] + btab[rel + 128];
;                     if (sample && kt == 8 && kl >= 32) v = -1e30f;
;                     s[sub][j] = v; mloc = fmaxf(mloc, v); }
;             }
.LBB0_827:
	s_or_b64 exec, exec, s[36:37]
	s_waitcnt lgkmcnt(0)
	s_barrier
	s_and_saveexec_b64 s[36:37], s[26:27]
	s_cbranch_execz .LBB0_802
	ds_read_b128 v[200:203], v190
	ds_read_b128 v[204:207], v190 offset:64
	ds_read_b128 v[208:211], v190 offset:128
	ds_read_b128 v[228:231], v190 offset:192
	ds_read_b128 v[232:235], v190 offset:4352
	ds_read_b128 v[236:239], v190 offset:4416
	ds_read_b128 v[240:243], v190 offset:4480
	ds_read_b128 v[244:247], v190 offset:4544
	ds_read_b128 v[248:251], v190 offset:8704
	ds_read_b128 v[50:53], v190 offset:8768
	s_mov_b64 s[38:39], -1
	s_cmp_lt_u32 s33, 6
	s_waitcnt lgkmcnt(9)
	v_mfma_f32_16x16x32_bf16 v[34:37], v[200:203], v[66:69], 0
	ds_read_b128 v[200:203], v190 offset:8832
	s_waitcnt lgkmcnt(9)
	v_mfma_f32_16x16x32_bf16 v[34:37], v[204:207], v[70:73], v[34:37]
	ds_read_b128 v[204:207], v190 offset:8896
	s_waitcnt lgkmcnt(9)
	v_mfma_f32_16x16x32_bf16 v[34:37], v[208:211], v[74:77], v[34:37]
	ds_read_b128 v[208:211], v190 offset:13056
	s_waitcnt lgkmcnt(9)
	v_mfma_f32_16x16x32_bf16 v[34:37], v[228:231], v[78:81], v[34:37]
	ds_read_b128 v[228:231], v190 offset:13120
	s_waitcnt lgkmcnt(9)
	v_mfma_f32_16x16x32_bf16 v[38:41], v[232:235], v[66:69], 0
	ds_read_b128 v[232:235], v190 offset:13184
	s_waitcnt lgkmcnt(9)
	v_mfma_f32_16x16x32_bf16 v[38:41], v[236:239], v[70:73], v[38:41]
	ds_read_b128 v[236:239], v190 offset:13248
	s_waitcnt lgkmcnt(9)
	v_mfma_f32_16x16x32_bf16 v[38:41], v[240:243], v[74:77], v[38:41]
	s_waitcnt lgkmcnt(8)
	v_mfma_f32_16x16x32_bf16 v[38:41], v[244:247], v[78:81], v[38:41]
	s_waitcnt lgkmcnt(7)
	v_mfma_f32_16x16x32_bf16 v[42:45], v[248:251], v[66:69], 0
	s_waitcnt lgkmcnt(6)
	v_mfma_f32_16x16x32_bf16 v[42:45], v[50:53], v[70:73], v[42:45]
	s_waitcnt lgkmcnt(5)
	v_mfma_f32_16x16x32_bf16 v[42:45], v[200:203], v[74:77], v[42:45]
	s_waitcnt lgkmcnt(4)
	v_mfma_f32_16x16x32_bf16 v[42:45], v[204:207], v[78:81], v[42:45]
	s_waitcnt lgkmcnt(3)
	v_mfma_f32_16x16x32_bf16 v[46:49], v[208:211], v[66:69], 0
	s_waitcnt lgkmcnt(2)
	v_mfma_f32_16x16x32_bf16 v[46:49], v[228:231], v[70:73], v[46:49]
	s_waitcnt lgkmcnt(1)
	v_mfma_f32_16x16x32_bf16 v[46:49], v[232:235], v[74:77], v[46:49]
	s_waitcnt lgkmcnt(0)
	v_mfma_f32_16x16x32_bf16 v[46:49], v[236:239], v[78:81], v[46:49]
	s_cbranch_scc1 .LBB0_830
	v_add_u32_e32 v1, s35, v186
	v_add_u32_e32 v1, 0x1000, v1
	v_mov_b32_e32 v50, s35
	v_cndmask_b32_e64 v1, v1, v50, s[4:5]
	v_add_u32_e32 v1, v1, v176
	v_sub_u32_e32 v62, v1, v153
	s_movk_i32 s38, 0xff80
	v_add_u32_e32 v51, -2, v62
	v_med3_i32 v51, v51, s38, v223
	v_lshl_add_u32 v52, v51, 2, v174
	v_add_u32_e32 v51, -3, v62
	v_med3_i32 v51, v51, s38, v223
	v_lshl_add_u32 v53, v51, 2, v174
	v_add_u32_e32 v51, -16, v62
	v_med3_i32 v51, v51, s38, v223
	v_lshl_add_u32 v54, v51, 2, v174
	v_subrev_u32_e32 v51, 17, v62
	v_med3_i32 v51, v51, s38, v223
	v_lshl_add_u32 v55, v51, 2, v174
	v_subrev_u32_e32 v51, 18, v62
	v_med3_i32 v51, v51, s38, v223
	v_med3_i32 v50, v62, s38, v223
	v_add_u32_e32 v1, v1, v180
	v_lshl_add_u32 v56, v51, 2, v174
	v_subrev_u32_e32 v51, 19, v62
	v_lshl_add_u32 v50, v50, 2, v174
	v_med3_i32 v1, v1, s38, v223
	v_med3_i32 v51, v51, s38, v223
	v_lshl_add_u32 v1, v1, 2, v174
	v_lshl_add_u32 v57, v51, 2, v174
	ds_read_b32 v50, v50 offset:512
	ds_read_b32 v51, v1 offset:512
	ds_read_b32 v52, v52 offset:512
	ds_read_b32 v53, v53 offset:512
	ds_read_b32 v58, v54 offset:512
	ds_read_b32 v59, v55 offset:512
	ds_read_b32 v60, v56 offset:512
	ds_read_b32 v61, v57 offset:512
	s_waitcnt lgkmcnt(4)
	v_pk_add_f32 v[54:55], v[36:37], v[52:53]
	v_subrev_u32_e32 v63, 48, v62
	s_waitcnt lgkmcnt(2)
	v_pk_add_f32 v[52:53], v[38:39], v[58:59]
	v_subrev_u32_e32 v58, 32, v62
	v_subrev_u32_e32 v59, 33, v62
	v_subrev_u32_e32 v64, 49, v62
	v_subrev_u32_e32 v65, 50, v62
	v_pk_add_f32 v[56:57], v[34:35], v[50:51]
	s_waitcnt lgkmcnt(0)
	v_pk_add_f32 v[50:51], v[40:41], v[60:61]
	v_med3_i32 v58, v58, s38, v223
	v_med3_i32 v59, v59, s38, v223
	v_subrev_u32_e32 v60, 34, v62
	v_subrev_u32_e32 v61, 35, v62
	v_med3_i32 v63, v63, s38, v223
	v_med3_i32 v64, v64, s38, v223
	v_med3_i32 v65, v65, s38, v223
	v_subrev_u32_e32 v62, 51, v62
	s_mov_b32 s39, 0xf149f2ca
	v_lshl_add_u32 v58, v58, 2, v174
	v_lshl_add_u32 v59, v59, 2, v174
	v_med3_i32 v60, v60, s38, v223
	v_med3_i32 v61, v61, s38, v223
	v_lshl_add_u32 v63, v63, 2, v174
	v_lshl_add_u32 v64, v64, 2, v174
	v_lshl_add_u32 v65, v65, 2, v174
	v_med3_i32 v62, v62, s38, v223
	v_max3_f32 v1, v56, s39, v57
	v_lshl_add_u32 v60, v60, 2, v174
	v_lshl_add_u32 v61, v61, 2, v174
	v_lshl_add_u32 v62, v62, 2, v174
	ds_read_b32 v58, v58 offset:512
	ds_read_b32 v59, v59 offset:512
	ds_read_b32 v171, v60 offset:512
	ds_read_b32 v173, v61 offset:512
	ds_read_b32 v63, v63 offset:512
	ds_read_b32 v64, v64 offset:512
	ds_read_b32 v65, v65 offset:512
	ds_read_b32 v192, v62 offset:512
	v_max3_f32 v1, v1, v54, v55
	s_waitcnt lgkmcnt(7)
	v_add_f32_e32 v58, v42, v58
	s_and_b64 vcc, s[4:5], vcc
	v_max3_f32 v1, v1, v52, v53
	v_cndmask_b32_e32 v60, v58, v224, vcc
	s_waitcnt lgkmcnt(6)
	v_add_f32_e32 v58, v43, v59
	v_max3_f32 v1, v1, v50, v51
	v_cndmask_b32_e32 v61, v58, v224, vcc
	s_waitcnt lgkmcnt(5)
	v_add_f32_e32 v58, v44, v171
	s_waitcnt lgkmcnt(4)
	v_add_f32_e32 v59, v45, v173
	v_max3_f32 v1, v1, v60, v61
	v_cndmask_b32_e32 v58, v58, v224, vcc
	v_cndmask_b32_e32 v59, v59, v224, vcc
	s_waitcnt lgkmcnt(3)
	v_add_f32_e32 v62, v46, v63
	s_waitcnt lgkmcnt(2)
	v_add_f32_e32 v63, v47, v64
	v_max3_f32 v1, v1, v58, v59
	v_cndmask_b32_e32 v62, v62, v224, vcc
	v_cndmask_b32_e32 v63, v63, v224, vcc
	s_waitcnt lgkmcnt(1)
	v_add_f32_e32 v64, v48, v65
	s_waitcnt lgkmcnt(0)
	v_add_f32_e32 v65, v49, v192
	v_max3_f32 v1, v1, v62, v63
	v_cndmask_b32_e32 v64, v64, v224, vcc
	v_cndmask_b32_e32 v65, v65, v224, vcc
	v_max3_f32 v1, v1, v64, v65
	s_mov_b64 s[38:39], 0
